# c15 + in-projection GEMM: next tile's As[1][1] DMA hoisted before the epilogue stores and a peeled first K iteration with waits relaxed over the 16 stores
# speedup vs baseline: 1.0014x; 1.0014x over previous
; #define PG8_STAGE(bufoff, gbase, voff) do { _Pragma("unroll") for (int _i = 0; _i < 2; ++_i) \
;         __builtin_amdgcn_global_load_lds((const unsigned*)((const char*)(gbase) + (voff)[_i]), (PG8_LAS unsigned*)(lds + (bufoff) + ldsw + _i * 8192), 16, 0, 0); } while (0)
; #define PG8_WAIT_V(n) asm volatile("s_waitcnt vmcnt(" #n ")" ::: "memory")
; #define PG8_BAR __builtin_amdgcn_s_barrier()
; template <class Epi, class Sched, bool ALIGN_EPI = false, bool SP2 = false>
; __device__ __forceinline__ void gemm_phase(PG8_LAS unsigned char* lds, const Gemm g, const Sched& S, const Epi& E) {
;     const int tid = threadIdx.x, wid = __builtin_amdgcn_readfirstlane(tid >> 6), lane = tid & 63, wr = wid >> 2, wc = wid & 3, fr = lane & 15, fq = lane >> 4;
;     const int K = g.K, nt = K / BK;
;     unsigned voffA[2], voffB[2];
; #pragma unroll
;     for (int i = 0; i < 2; ++i) { int R, C; stage_rc(tid * 16 + i * 8192, R, C); const int Rb = Epi::PERM ? ((R & ~31) + perm32(R & 31)) : R;
;         voffA[i] = (unsigned)(R * K + C) * 2u; voffB[i] = (unsigned)(Rb * K + C) * 2u; }
;     const size_t kstep = (size_t)(BK * 2);
;     const size_t hstep = (size_t)HALF * K * 2;
;     const size_t tstep = 2 * hstep;
;     const unsigned ldsw = (unsigned)wid * 1024u;
;     const int aoff = lds_byte(wr * 64 + fr, fq * 8), boff = lds_byte(wc * 32 + fr, fq * 8);
;     ...
;         PG8_WAIT_V(2); PG8_BAR;
;         PG8_STAGE(PG8_SB(1, 0), cB + kstep, voffB); PG8_STAGE(PG8_SA(1, 0), cA + kstep, voffA); PG8_STAGE(PG8_SB(1, 1), cB + hstep + kstep, voffB);
;         PG8_WAIT_V(6); PG8_BAR;
.LBB0_178:
	s_mov_b64 s[16:17], 0x80
	s_and_b32 s3, s3, 3
	s_add_i32 m0, s50, 0x18000
	v_lshl_add_u64 v[6:7], v[6:7], 0, s[16:17]
	s_lshl_b32 s55, s4, 6
	s_lshl_b32 s7, s4, 13
	s_waitcnt lgkmcnt(0)
	s_lshl_b32 s66, s3, 5
	s_lshl_b32 s10, s3, 12
	s_waitcnt vmcnt(2)
	s_barrier
	global_load_lds_dwordx4 v[6:7], off
	v_lshl_add_u64 v[4:5], v[4:5], 0, s[16:17]
	s_add_i32 m0, s50, 0x1a000
	s_add_i32 s67, s50, 0x8000
	s_add_i32 s68, s50, 0xa000
	global_load_lds_dwordx4 v[4:5], off
	v_lshl_add_u64 v[2:3], v[2:3], 0, s[16:17]
	s_mov_b32 m0, s67
	s_add_u32 s4, s42, 0x80080
	global_load_lds_dwordx4 v[2:3], off
	v_lshl_add_u64 v[0:1], v[0:1], 0, s[16:17]
	s_mov_b32 m0, s68
	s_addc_u32 s5, s43, 0
	global_load_lds_dwordx4 v[0:1], off
	s_add_i32 m0, s50, 0x1c000
	v_lshl_add_u64 v[0:1], s[4:5], 0, v[136:137]
	global_load_lds_dwordx4 v[0:1], off
	v_lshl_add_u64 v[0:1], s[4:5], 0, v[140:141]
	s_add_i32 m0, s50, 0x1e000
	s_cmpk_lt_u32 s1, 0x100
	global_load_lds_dwordx4 v[0:1], off
	v_bfe_u32 v14, v161, 4, 2
	s_cselect_b64 s[18:19], -1, 0
	s_add_u32 s69, s94, 0x18700000
	v_and_b32_e32 v13, 15, v161
	v_lshlrev_b32_e32 v0, 4, v14
	v_lshlrev_b32_e32 v2, 2, v161
	s_addc_u32 s70, s95, 0
	v_lshl_or_b32 v1, v13, 6, v0
	v_and_b32_e32 v2, 32, v2
	s_add_u32 s71, s94, 0x100000
	v_bitop3_b32 v3, v1, s7, v2 bitop3:0xde
	v_lshlrev_b32_e32 v1, 6, v161
	s_movk_i32 s4, 0x3c0
	s_addc_u32 s78, s95, 0
	s_lshl_b32 s1, s3, 11
	v_lshrrev_b32_e32 v12, 4, v161
	v_and_or_b32 v0, v1, s4, v0
	s_add_i32 s1, s1, 0
	v_bitop3_b32 v159, s10, v0, v2 bitop3:0xf6
	s_add_i32 s1, s1, s7
	v_and_b32_e32 v163, 31, v161
	v_bfe_u32 v0, v12, 1, 1
	s_add_i32 s1, s1, 0x20000
	v_mul_u32_u24_e32 v2, 48, v163
	v_lshlrev_b32_e32 v4, 4, v0
	v_lshlrev_b32_e32 v1, 1, v13
	v_add3_u32 v164, s1, v2, v4
	v_mul_u32_u24_e32 v2, 0x180, v14
	v_add3_u32 v166, s1, v1, v2
	v_lshlrev_b32_e32 v1, 4, v163
	v_lshlrev_b32_e32 v142, 5, v14
	v_lshl_or_b32 v165, v0, 3, s55
	v_lshl_or_b32 v144, v0, 9, v1
	v_lshl_add_u64 v[0:1], s[94:95], 0, v[142:143]
	s_mov_b64 s[4:5], 0x38f00000
	v_lshl_add_u64 v[146:147], v[0:1], 0, s[4:5]
	v_lshlrev_b32_e32 v0, 9, v161
	v_and_b32_e32 v0, 0x70000, v0
	v_lshlrev_b32_e32 v1, 12, v10
	v_or3_b32 v0, v8, v0, v1
	s_add_i32 s79, s55, 0x80
	v_add_u32_e32 v148, v0, v9
	v_lshlrev_b32_e32 v0, 5, v11
	s_waitcnt vmcnt(6)
	s_cmp_eq_u32 s3, 0
	v_and_b32_e32 v0, 0xf0000, v0
	s_cselect_b64 s[20:21], -1, 0
	v_or3_b32 v0, v8, v0, v1
	s_add_i32 s82, 0, 0x10000
	s_add_i32 s83, 0, 0x14000
	v_or_b32_e32 v158, s55, v13
	v_lshl_or_b32 v162, v14, 3, s66
	v_mov_b32_e32 v145, v143
	v_or_b32_e32 v167, 16, v165
	v_or_b32_e32 v168, 32, v165
	v_or_b32_e32 v169, 48, v165
	v_add_u32_e32 v170, 0x80, v165
	v_add_u32_e32 v171, 0x90, v165
	v_add_u32_e32 v172, 0xa0, v165
	v_add_u32_e32 v173, 0xb0, v165
	s_ashr_i32 s80, s46, 31
	s_ashr_i32 s81, s2, 31
	v_mov_b32_e32 v149, v143
	v_add_u32_e32 v150, v0, v9
	v_mov_b32_e32 v151, v143
	v_mov_b64_e32 v[152:153], 0x1cf2
	v_mov_b64_e32 v[154:155], 0x1cf1
	v_add_u32_e32 v174, s82, v159
	v_add_u32_e32 v175, s83, v159
	v_add_u32_e32 v176, 0, v3
	s_mov_b64 s[22:23], 0x4000
	s_mov_b64 s[24:25], 0x4800
	s_mov_b64 s[26:27], 0x5000
	s_mov_b64 s[28:29], 0x5800
	s_mov_b32 s84, 0
	s_mov_b32 s58, 0
	s_barrier
	s_branch .LBB0_181

; #define PG8_STAGE(bufoff, gbase, voff) do { _Pragma("unroll") for (int _i = 0; _i < 2; ++_i) \
;         __builtin_amdgcn_global_load_lds((const unsigned*)((const char*)(gbase) + (voff)[_i]), (PG8_LAS unsigned*)(lds + (bufoff) + ldsw + _i * 8192), 16, 0, 0); } while (0)
; #define PG8_LDA(dst, b, h) do { _Pragma("unroll") for (int m = 0; m < 4; ++m) _Pragma("unroll") for (int k = 0; k < 2; ++k) dst[m][k] = *(const PG8_LAS bf16x8*)(lds + PG8_SA(b, h) + aoff + m * 2048 + k * 1024); } while (0)
; #define PG8_LDB(dst, b, h) do { _Pragma("unroll") for (int n = 0; n < 2; ++n) _Pragma("unroll") for (int k = 0; k < 2; ++k) dst[n][k] = *(const PG8_LAS bf16x8*)(lds + PG8_SB(b, h) + boff + n * 2048 + k * 1024); } while (0)
; #define PG8_MMA(ai, bj, At, Bt) do { __builtin_amdgcn_s_setprio(1); _Pragma("unroll") for (int m = 0; m < 4; ++m) _Pragma("unroll") for (int n = 0; n < 2; ++n) _Pragma("unroll") for (int k = 0; k < 2; ++k) \
;         acc[ai][bj][m][n] = __builtin_amdgcn_mfma_f32_16x16x32_bf16(Bt[n][k], At[m][k], acc[ai][bj][m][n], 0, 0, 0); __builtin_amdgcn_s_setprio(0); } while (0)
; #define PG8_WAIT_V(n) asm volatile("s_waitcnt vmcnt(" #n ")" ::: "memory")
; #define PG8_WAIT_L(n) asm volatile("s_waitcnt lgkmcnt(" #n ")" ::: "memory")
; #define PG8_BAR __builtin_amdgcn_s_barrier()
; #define PG8_SCHED __builtin_amdgcn_sched_barrier(0)
; template <class Epi, class Sched, bool ALIGN_EPI = false, bool SP2 = false>
; __device__ __forceinline__ void gemm_phase(PG8_LAS unsigned char* lds, const Gemm g, const Sched& S, const Epi& E) {
;     ...
;             PG8_LDB(B0, 0, 0); PG8_LDB(B1, 0, 1); PG8_SCHED; PG8_LDA(At, 0, 0); PG8_STAGE(PG8_SA(1, 1), a1 + hstep, voffA);
;             PG8_WAIT_V(8); PG8_WAIT_L(0); PG8_BAR; PG8_MMA(0, 0, At, B0); PG8_MMA(0, 1, At, B1); PG8_BAR; PG8_SCHED;
;     ...
; #pragma unroll
;         for (int a = 0; a < 2; ++a)
; #pragma unroll
;             for (int b = 0; b < 2; ++b)
; #pragma unroll
;                 for (int m = 0; m < 4; ++m)
; #pragma unroll
;                     for (int n = 0; n < 2; ++n) acc[a][b][m][n] = (f32x4){0.f, 0.f, 0.f, 0.f};
;         cur = nxt; cA = nA; cB = nB; ++ui;
.LBB0_187:
	s_cmp_lg_u32 s6, 56
	s_cselect_b32 s32, 1, 0
	s_and_b32 vcc_lo, s0, 3
	s_lshl_b32 vcc_lo, vcc_lo, 12
	s_mul_i32 vcc_lo, vcc_lo, s32
	s_mulk_i32 s32, 0x3000
	s_sub_i32 s32, vcc_lo, s32
	v_add_u32_e32 v177, vcc_lo, v159
	v_add_u32_e32 v244, s32, v159
	v_add_u32_e32 v174, s82, v177
	v_add_u32_e32 v175, s83, v244
	s_ashr_i32 s35, s34, 31
	s_lshl_b64 s[36:37], s[34:35], 20
	s_add_u32 s36, s92, s36
	s_addc_u32 s37, s93, s37
	s_ashr_i32 s31, s30, 31
	s_lshl_b64 s[38:39], s[30:31], 20
	s_add_u32 s38, s47, s38
	s_addc_u32 s39, s48, s39
	s_and_b32 s1, s30, -4
	s_cmp_eq_u32 s1, 8
	s_cselect_b32 s1, 1, 0
	s_and_b32 s3, s30, -8
	s_cmp_eq_u32 s3, 24
	s_cselect_b32 s1, 1, s1
	s_cmp_lg_u32 s1, 0
	s_cselect_b32 s1, s38, s36
	s_cselect_b32 s3, s39, s37
	s_cselect_b32 s38, s36, s38
	s_cselect_b32 s39, s37, s39
	s_mov_b32 s36, s1
	s_mov_b32 s37, s3
	s_and_b64 s[44:45], s[4:5], exec
	s_cselect_b32 s1, s37, s41
	s_cselect_b32 s3, s36, s40
	s_cselect_b32 s7, s39, s43
	s_cselect_b32 s10, s38, s42
	s_add_u32 s40, s40, 0x80080
	s_addc_u32 s41, s41, 0
	s_add_u32 s13, s42, 0x100
	s_waitcnt lgkmcnt(0)
	v_mov_b32_e32 v66, 0
	s_addc_u32 s31, s43, 0
	s_mov_b32 s33, -2
	v_mov_b32_e32 v67, v66
	v_mov_b32_e32 v68, v66
	v_mov_b32_e32 v69, v66
	v_mov_b32_e32 v74, v66
	v_mov_b32_e32 v75, v66
	v_mov_b32_e32 v76, v66
	v_mov_b32_e32 v77, v66
	v_mov_b32_e32 v70, v66
	v_mov_b32_e32 v71, v66
	v_mov_b32_e32 v72, v66
	v_mov_b32_e32 v73, v66
	v_mov_b32_e32 v78, v66
	v_mov_b32_e32 v79, v66
	v_mov_b32_e32 v80, v66
	v_mov_b32_e32 v81, v66
	v_mov_b32_e32 v82, v66
	v_mov_b32_e32 v83, v66
	v_mov_b32_e32 v84, v66
	v_mov_b32_e32 v85, v66
	v_mov_b32_e32 v86, v66
	v_mov_b32_e32 v87, v66
	v_mov_b32_e32 v88, v66
	v_mov_b32_e32 v89, v66
	v_mov_b32_e32 v90, v66
	v_mov_b32_e32 v91, v66
	v_mov_b32_e32 v92, v66
	v_mov_b32_e32 v93, v66
	v_mov_b32_e32 v94, v66
	v_mov_b32_e32 v95, v66
	v_mov_b32_e32 v96, v66
	v_mov_b32_e32 v97, v66
	v_mov_b32_e32 v0, v66
	v_mov_b32_e32 v1, v66
	v_mov_b32_e32 v2, v66
	v_mov_b32_e32 v3, v66
	v_mov_b32_e32 v4, v66
	v_mov_b32_e32 v5, v66
	v_mov_b32_e32 v6, v66
	v_mov_b32_e32 v7, v66
	v_mov_b32_e32 v8, v66
	v_mov_b32_e32 v9, v66
	v_mov_b32_e32 v10, v66
	v_mov_b32_e32 v11, v66
	v_mov_b32_e32 v12, v66
	v_mov_b32_e32 v13, v66
	v_mov_b32_e32 v14, v66
	v_mov_b32_e32 v15, v66
	v_mov_b32_e32 v16, v66
	v_mov_b32_e32 v17, v66
	v_mov_b32_e32 v18, v66
	v_mov_b32_e32 v19, v66
	v_mov_b32_e32 v20, v66
	v_mov_b32_e32 v21, v66
	v_mov_b32_e32 v22, v66
	v_mov_b32_e32 v23, v66
	v_mov_b32_e32 v24, v66
	v_mov_b32_e32 v25, v66
	v_mov_b32_e32 v26, v66
	v_mov_b32_e32 v27, v66
	v_mov_b32_e32 v28, v66
	v_mov_b32_e32 v29, v66
	v_mov_b32_e32 v30, v66
	v_mov_b32_e32 v31, v66
	v_mov_b32_e32 v98, v66
	v_mov_b32_e32 v99, v66
	v_mov_b32_e32 v100, v66
	v_mov_b32_e32 v101, v66
	v_mov_b32_e32 v102, v66
	v_mov_b32_e32 v103, v66
	v_mov_b32_e32 v104, v66
	v_mov_b32_e32 v105, v66
	v_mov_b32_e32 v106, v66
	v_mov_b32_e32 v107, v66
	v_mov_b32_e32 v108, v66
	v_mov_b32_e32 v109, v66
	v_mov_b32_e32 v110, v66
	v_mov_b32_e32 v111, v66
	v_mov_b32_e32 v112, v66
	v_mov_b32_e32 v113, v66
	v_mov_b32_e32 v114, v66
	v_mov_b32_e32 v115, v66
	v_mov_b32_e32 v116, v66
	v_mov_b32_e32 v117, v66
	v_mov_b32_e32 v118, v66
	v_mov_b32_e32 v119, v66
	v_mov_b32_e32 v120, v66
	v_mov_b32_e32 v121, v66
	v_mov_b32_e32 v122, v66
	v_mov_b32_e32 v123, v66
	v_mov_b32_e32 v124, v66
	v_mov_b32_e32 v125, v66
	v_mov_b32_e32 v126, v66
	v_mov_b32_e32 v127, v66
	v_mov_b32_e32 v128, v66
	v_mov_b32_e32 v129, v66
	v_mov_b32_e32 v32, v66
	v_mov_b32_e32 v33, v66
	v_mov_b32_e32 v34, v66
	v_mov_b32_e32 v35, v66
	v_mov_b32_e32 v36, v66
	v_mov_b32_e32 v37, v66
	v_mov_b32_e32 v38, v66
	v_mov_b32_e32 v39, v66
	v_mov_b32_e32 v40, v66
	v_mov_b32_e32 v41, v66
	v_mov_b32_e32 v42, v66
	v_mov_b32_e32 v43, v66
	v_mov_b32_e32 v44, v66
	v_mov_b32_e32 v45, v66
	v_mov_b32_e32 v46, v66
	v_mov_b32_e32 v47, v66
	v_mov_b32_e32 v48, v66
	v_mov_b32_e32 v49, v66
	v_mov_b32_e32 v50, v66
	v_mov_b32_e32 v51, v66
	v_mov_b32_e32 v52, v66
	v_mov_b32_e32 v53, v66
	v_mov_b32_e32 v54, v66
	v_mov_b32_e32 v55, v66
	v_mov_b32_e32 v56, v66
	v_mov_b32_e32 v57, v66
	v_mov_b32_e32 v58, v66
	v_mov_b32_e32 v59, v66
	v_mov_b32_e32 v60, v66
	v_mov_b32_e32 v61, v66
	v_mov_b32_e32 v62, v66
	v_mov_b32_e32 v63, v66
	s_cmp_eq_u32 s58, 0
	s_cbranch_scc1 .LBB0_188
	s_mov_b32 s58, 0
	ds_read_b128 v[130:133], v174
	ds_read_b128 v[178:181], v174 offset:1024
	ds_read_b128 v[182:185], v174 offset:2048
	ds_read_b128 v[186:189], v174 offset:3072
	ds_read_b128 v[190:193], v175
	ds_read_b128 v[194:197], v175 offset:1024
	ds_read_b128 v[198:201], v175 offset:2048
	ds_read_b128 v[202:205], v175 offset:3072
	s_add_u32 s35, s40, 0xfff80080
	s_addc_u32 s42, s41, -1
	s_cmp_eq_u32 s33, 28
	s_cselect_b32 s45, s1, s42
	s_cselect_b32 s44, s3, s35
	s_cselect_b32 s43, s7, s31
	s_cselect_b32 s42, s10, s13
	ds_read_b128 v[206:209], v176
	ds_read_b128 v[210:213], v176 offset:1024
	ds_read_b128 v[214:217], v176 offset:2048
	ds_read_b128 v[218:221], v176 offset:3072
	ds_read_b128 v[222:225], v176 offset:4096
	ds_read_b128 v[226:229], v176 offset:5120
	ds_read_b128 v[230:233], v176 offset:6144
	ds_read_b128 v[234:237], v176 offset:7168
	s_waitcnt vmcnt(24)
	s_waitcnt lgkmcnt(0)
	s_barrier
; #define PG8_STAGE(bufoff, gbase, voff) do { _Pragma("unroll") for (int _i = 0; _i < 2; ++_i) \
;         __builtin_amdgcn_global_load_lds((const unsigned*)((const char*)(gbase) + (voff)[_i]), (PG8_LAS unsigned*)(lds + (bufoff) + ldsw + _i * 8192), 16, 0, 0); } while (0)
; #define PG8_LDA(dst, b, h) do { _Pragma("unroll") for (int m = 0; m < 4; ++m) _Pragma("unroll") for (int k = 0; k < 2; ++k) dst[m][k] = *(const PG8_LAS bf16x8*)(lds + PG8_SA(b, h) + aoff + m * 2048 + k * 1024); } while (0)
; #define PG8_MMA(ai, bj, At, Bt) do { __builtin_amdgcn_s_setprio(1); _Pragma("unroll") for (int m = 0; m < 4; ++m) _Pragma("unroll") for (int n = 0; n < 2; ++n) _Pragma("unroll") for (int k = 0; k < 2; ++k) \
;         acc[ai][bj][m][n] = __builtin_amdgcn_mfma_f32_16x16x32_bf16(Bt[n][k], At[m][k], acc[ai][bj][m][n], 0, 0, 0); __builtin_amdgcn_s_setprio(0); } while (0)
; #define PG8_WAIT_V(n) asm volatile("s_waitcnt vmcnt(" #n ")" ::: "memory")
; #define PG8_WAIT_L(n) asm volatile("s_waitcnt lgkmcnt(" #n ")" ::: "memory")
; #define PG8_BAR __builtin_amdgcn_s_barrier()
; #define PG8_SCHED __builtin_amdgcn_sched_barrier(0)
; template <class Epi, class Sched, bool ALIGN_EPI = false, bool SP2 = false>
; __device__ __forceinline__ void gemm_phase(PG8_LAS unsigned char* lds, const Gemm g, const Sched& S, const Epi& E) {
;     ...
;             PG8_WAIT_V(8); PG8_WAIT_L(0); PG8_BAR; PG8_MMA(0, 0, At, B0); PG8_MMA(0, 1, At, B1); PG8_BAR; PG8_SCHED;
;             PG8_LDA(At, 0, 1); PG8_STAGE(PG8_SB(0, 0), b2, voffB); PG8_STAGE(PG8_SB(0, 1), b2 + hstep, voffB); PG8_STAGE(PG8_SA(0, 0), a2, voffA);
;             PG8_WAIT_V(8); PG8_WAIT_L(0); PG8_BAR; PG8_MMA(1, 0, At, B0); PG8_MMA(1, 1, At, B1); PG8_BAR; PG8_SCHED;
	s_setprio 1
	s_waitcnt lgkmcnt(0)
	v_mfma_f32_16x16x32_bf16 v[60:63], v[130:133], v[206:209], v[60:63]
	v_mfma_f32_16x16x32_bf16 v[56:59], v[182:185], v[206:209], v[56:59]
	v_mfma_f32_16x16x32_bf16 v[52:55], v[130:133], v[214:217], v[52:55]
	v_mfma_f32_16x16x32_bf16 v[48:51], v[182:185], v[214:217], v[48:51]
	v_mfma_f32_16x16x32_bf16 v[44:47], v[130:133], v[222:225], v[44:47]
	v_mfma_f32_16x16x32_bf16 v[40:43], v[182:185], v[222:225], v[40:43]
	v_mfma_f32_16x16x32_bf16 v[36:39], v[130:133], v[230:233], v[36:39]
	v_mfma_f32_16x16x32_bf16 v[32:35], v[182:185], v[230:233], v[32:35]
	v_mfma_f32_16x16x32_bf16 v[60:63], v[178:181], v[210:213], v[60:63]
	v_mfma_f32_16x16x32_bf16 v[56:59], v[186:189], v[210:213], v[56:59]
	v_mfma_f32_16x16x32_bf16 v[52:55], v[178:181], v[218:221], v[52:55]
	v_mfma_f32_16x16x32_bf16 v[48:51], v[186:189], v[218:221], v[48:51]
	v_mfma_f32_16x16x32_bf16 v[44:47], v[178:181], v[226:229], v[44:47]
	v_mfma_f32_16x16x32_bf16 v[40:43], v[186:189], v[226:229], v[40:43]
	v_mfma_f32_16x16x32_bf16 v[36:39], v[178:181], v[234:237], v[36:39]
	v_mfma_f32_16x16x32_bf16 v[32:35], v[186:189], v[234:237], v[32:35]
	s_setprio 0
	s_setprio 1
	v_mfma_f32_16x16x32_bf16 v[126:129], v[190:193], v[206:209], v[126:129]
	v_mfma_f32_16x16x32_bf16 v[122:125], v[198:201], v[206:209], v[122:125]
	v_mfma_f32_16x16x32_bf16 v[118:121], v[190:193], v[214:217], v[118:121]
	v_mfma_f32_16x16x32_bf16 v[114:117], v[198:201], v[214:217], v[114:117]
	v_mfma_f32_16x16x32_bf16 v[110:113], v[190:193], v[222:225], v[110:113]
	v_mfma_f32_16x16x32_bf16 v[106:109], v[198:201], v[222:225], v[106:109]
	v_mfma_f32_16x16x32_bf16 v[102:105], v[190:193], v[230:233], v[102:105]
	v_mfma_f32_16x16x32_bf16 v[98:101], v[198:201], v[230:233], v[98:101]
	v_mfma_f32_16x16x32_bf16 v[126:129], v[194:197], v[210:213], v[126:129]
	v_mfma_f32_16x16x32_bf16 v[122:125], v[202:205], v[210:213], v[122:125]
	v_mfma_f32_16x16x32_bf16 v[118:121], v[194:197], v[218:221], v[118:121]
	v_mfma_f32_16x16x32_bf16 v[114:117], v[202:205], v[218:221], v[114:117]
	v_mfma_f32_16x16x32_bf16 v[110:113], v[194:197], v[226:229], v[110:113]
	v_mfma_f32_16x16x32_bf16 v[106:109], v[202:205], v[226:229], v[106:109]
	v_mfma_f32_16x16x32_bf16 v[102:105], v[194:197], v[234:237], v[102:105]
	v_mfma_f32_16x16x32_bf16 v[98:101], v[202:205], v[234:237], v[98:101]
	s_setprio 0
	s_barrier
	s_add_i32 s35, s82, s49
	v_lshl_add_u64 v[156:157], s[42:43], 0, v[136:137]
	s_mov_b32 m0, s35
	ds_read_b128 v[206:209], v176 offset:16384
	ds_read_b128 v[210:213], v176 offset:17408
	ds_read_b128 v[214:217], v176 offset:18432
	ds_read_b128 v[218:221], v176 offset:19456
	ds_read_b128 v[222:225], v176 offset:20480
	ds_read_b128 v[226:229], v176 offset:21504
	ds_read_b128 v[230:233], v176 offset:22528
	ds_read_b128 v[234:237], v176 offset:23552
	global_load_lds_dwordx4 v[156:157], off
	s_add_i32 m0, s35, 0x2000
	s_add_u32 s56, s42, 0x80000
	v_lshl_add_u64 v[238:239], s[42:43], 0, v[140:141]
	s_addc_u32 s57, s43, 0
	s_add_i32 s35, s83, s49
	global_load_lds_dwordx4 v[238:239], off
	v_lshl_add_u64 v[64:65], s[56:57], 0, v[136:137]
	s_mov_b32 m0, s35
	v_lshl_add_u64 v[240:241], s[44:45], 0, v[134:135]
	global_load_lds_dwordx4 v[64:65], off
	v_lshl_add_u64 v[64:65], s[56:57], 0, v[140:141]
	s_add_i32 m0, s35, 0x2000
	v_lshl_add_u64 v[242:243], s[44:45], 0, v[138:139]
	global_load_lds_dwordx4 v[64:65], off
	s_mov_b32 m0, s50
	s_nop 0
	global_load_lds_dwordx4 v[240:241], off
	s_mov_b32 m0, s51
	s_nop 0
	global_load_lds_dwordx4 v[242:243], off
	s_waitcnt vmcnt(24)
	s_waitcnt lgkmcnt(0)
	s_barrier
	s_setprio 1
	s_waitcnt lgkmcnt(0)
	v_mfma_f32_16x16x32_bf16 v[28:31], v[130:133], v[206:209], v[28:31]
	v_mfma_f32_16x16x32_bf16 v[24:27], v[182:185], v[206:209], v[24:27]
	v_mfma_f32_16x16x32_bf16 v[20:23], v[130:133], v[214:217], v[20:23]
	v_mfma_f32_16x16x32_bf16 v[16:19], v[182:185], v[214:217], v[16:19]
	v_mfma_f32_16x16x32_bf16 v[12:15], v[130:133], v[222:225], v[12:15]
	v_mfma_f32_16x16x32_bf16 v[8:11], v[182:185], v[222:225], v[8:11]
	v_mfma_f32_16x16x32_bf16 v[4:7], v[130:133], v[230:233], v[4:7]
	v_mfma_f32_16x16x32_bf16 v[0:3], v[182:185], v[230:233], v[0:3]
	v_mfma_f32_16x16x32_bf16 v[28:31], v[178:181], v[210:213], v[28:31]
	v_mfma_f32_16x16x32_bf16 v[24:27], v[186:189], v[210:213], v[24:27]
	v_mfma_f32_16x16x32_bf16 v[20:23], v[178:181], v[218:221], v[20:23]
	v_mfma_f32_16x16x32_bf16 v[16:19], v[186:189], v[218:221], v[16:19]
	v_mfma_f32_16x16x32_bf16 v[12:15], v[178:181], v[226:229], v[12:15]
	v_mfma_f32_16x16x32_bf16 v[8:11], v[186:189], v[226:229], v[8:11]
	v_mfma_f32_16x16x32_bf16 v[4:7], v[178:181], v[234:237], v[4:7]
	v_mfma_f32_16x16x32_bf16 v[0:3], v[186:189], v[234:237], v[0:3]
	s_setprio 0
	s_setprio 1
	v_mfma_f32_16x16x32_bf16 v[94:97], v[190:193], v[206:209], v[94:97]
	v_mfma_f32_16x16x32_bf16 v[90:93], v[198:201], v[206:209], v[90:93]
	v_mfma_f32_16x16x32_bf16 v[86:89], v[190:193], v[214:217], v[86:89]
	v_mfma_f32_16x16x32_bf16 v[82:85], v[198:201], v[214:217], v[82:85]
	v_mfma_f32_16x16x32_bf16 v[78:81], v[190:193], v[222:225], v[78:81]
	v_mfma_f32_16x16x32_bf16 v[70:73], v[198:201], v[222:225], v[70:73]
	v_mfma_f32_16x16x32_bf16 v[74:77], v[190:193], v[230:233], v[74:77]
	v_mfma_f32_16x16x32_bf16 v[64:67], v[198:201], v[230:233], v[66:69]
	v_mfma_f32_16x16x32_bf16 v[94:97], v[194:197], v[210:213], v[94:97]
	v_mfma_f32_16x16x32_bf16 v[90:93], v[202:205], v[210:213], v[90:93]
	v_mfma_f32_16x16x32_bf16 v[86:89], v[194:197], v[218:221], v[86:89]
	v_mfma_f32_16x16x32_bf16 v[82:85], v[202:205], v[218:221], v[82:85]
	v_mfma_f32_16x16x32_bf16 v[78:81], v[194:197], v[226:229], v[78:81]
	v_mfma_f32_16x16x32_bf16 v[70:73], v[202:205], v[226:229], v[70:73]
	v_mfma_f32_16x16x32_bf16 v[74:77], v[194:197], v[234:237], v[74:77]
	v_mfma_f32_16x16x32_bf16 v[64:67], v[202:205], v[234:237], v[64:67]
	s_setprio 0
	s_barrier
; #define PG8_STAGE(bufoff, gbase, voff) do { _Pragma("unroll") for (int _i = 0; _i < 2; ++_i) \
;         __builtin_amdgcn_global_load_lds((const unsigned*)((const char*)(gbase) + (voff)[_i]), (PG8_LAS unsigned*)(lds + (bufoff) + ldsw + _i * 8192), 16, 0, 0); } while (0)
; #define PG8_LDA(dst, b, h) do { _Pragma("unroll") for (int m = 0; m < 4; ++m) _Pragma("unroll") for (int k = 0; k < 2; ++k) dst[m][k] = *(const PG8_LAS bf16x8*)(lds + PG8_SA(b, h) + aoff + m * 2048 + k * 1024); } while (0)
; #define PG8_LDB(dst, b, h) do { _Pragma("unroll") for (int n = 0; n < 2; ++n) _Pragma("unroll") for (int k = 0; k < 2; ++k) dst[n][k] = *(const PG8_LAS bf16x8*)(lds + PG8_SB(b, h) + boff + n * 2048 + k * 1024); } while (0)
; #define PG8_MMA(ai, bj, At, Bt) do { __builtin_amdgcn_s_setprio(1); _Pragma("unroll") for (int m = 0; m < 4; ++m) _Pragma("unroll") for (int n = 0; n < 2; ++n) _Pragma("unroll") for (int k = 0; k < 2; ++k) \
;         acc[ai][bj][m][n] = __builtin_amdgcn_mfma_f32_16x16x32_bf16(Bt[n][k], At[m][k], acc[ai][bj][m][n], 0, 0, 0); __builtin_amdgcn_s_setprio(0); } while (0)
; #define PG8_WAIT_V(n) asm volatile("s_waitcnt vmcnt(" #n ")" ::: "memory")
; #define PG8_WAIT_L(n) asm volatile("s_waitcnt lgkmcnt(" #n ")" ::: "memory")
; #define PG8_BAR __builtin_amdgcn_s_barrier()
; #define PG8_SCHED __builtin_amdgcn_sched_barrier(0)
; template <class Epi, class Sched, bool ALIGN_EPI = false, bool SP2 = false>
; __device__ __forceinline__ void gemm_phase(PG8_LAS unsigned char* lds, const Gemm g, const Sched& S, const Epi& E) {
;     ...
;             PG8_LDB(B0, 1, 0); PG8_LDB(B1, 1, 1); PG8_SCHED; PG8_LDA(At, 1, 0); PG8_STAGE(PG8_SA(0, 1), a2 + hstep, voffA);
;             PG8_WAIT_V(8); PG8_WAIT_L(0); PG8_BAR; PG8_MMA(0, 0, At, B0); PG8_MMA(0, 1, At, B1); PG8_BAR; PG8_SCHED;
	s_add_i32 s35, 0, 0x18000
	v_add_u32_e32 v68, s35, v177
	s_add_i32 s56, 0, 0x1c000
	ds_read_b128 v[130:133], v68
	ds_read_b128 v[178:181], v68 offset:1024
	ds_read_b128 v[182:185], v68 offset:2048
	ds_read_b128 v[186:189], v68 offset:3072
	v_add_u32_e32 v68, s56, v244
	ds_read_b128 v[190:193], v68
	ds_read_b128 v[194:197], v68 offset:1024
	ds_read_b128 v[198:201], v68 offset:2048
	ds_read_b128 v[202:205], v68 offset:3072
	s_add_u32 s44, s44, 0x80000
	s_addc_u32 s45, s45, 0
	s_mov_b32 m0, s52
	v_lshl_add_u64 v[68:69], s[44:45], 0, v[134:135]
	ds_read_b128 v[206:209], v176 offset:32768
	ds_read_b128 v[210:213], v176 offset:33792
	ds_read_b128 v[214:217], v176 offset:34816
	ds_read_b128 v[218:221], v176 offset:35840
	ds_read_b128 v[222:225], v176 offset:36864
	ds_read_b128 v[226:229], v176 offset:37888
	ds_read_b128 v[230:233], v176 offset:38912
	ds_read_b128 v[234:237], v176 offset:39936
	global_load_lds_dwordx4 v[68:69], off
	v_lshl_add_u64 v[68:69], s[44:45], 0, v[138:139]
	s_mov_b32 m0, s53
	s_nop 0
	global_load_lds_dwordx4 v[68:69], off
	s_waitcnt vmcnt(24)
	s_waitcnt lgkmcnt(0)
	s_barrier
	s_setprio 1
	s_waitcnt lgkmcnt(0)
	v_mfma_f32_16x16x32_bf16 v[60:63], v[130:133], v[206:209], v[60:63]
	v_mfma_f32_16x16x32_bf16 v[56:59], v[182:185], v[206:209], v[56:59]
	v_mfma_f32_16x16x32_bf16 v[52:55], v[130:133], v[214:217], v[52:55]
	v_mfma_f32_16x16x32_bf16 v[48:51], v[182:185], v[214:217], v[48:51]
	v_mfma_f32_16x16x32_bf16 v[44:47], v[130:133], v[222:225], v[44:47]
	v_mfma_f32_16x16x32_bf16 v[40:43], v[182:185], v[222:225], v[40:43]
	v_mfma_f32_16x16x32_bf16 v[36:39], v[130:133], v[230:233], v[36:39]
	v_mfma_f32_16x16x32_bf16 v[32:35], v[182:185], v[230:233], v[32:35]
	v_mfma_f32_16x16x32_bf16 v[60:63], v[178:181], v[210:213], v[60:63]
	v_mfma_f32_16x16x32_bf16 v[56:59], v[186:189], v[210:213], v[56:59]
	v_mfma_f32_16x16x32_bf16 v[52:55], v[178:181], v[218:221], v[52:55]
	v_mfma_f32_16x16x32_bf16 v[48:51], v[186:189], v[218:221], v[48:51]
	v_mfma_f32_16x16x32_bf16 v[44:47], v[178:181], v[226:229], v[44:47]
	v_mfma_f32_16x16x32_bf16 v[40:43], v[186:189], v[226:229], v[40:43]
	v_mfma_f32_16x16x32_bf16 v[36:39], v[178:181], v[234:237], v[36:39]
	v_mfma_f32_16x16x32_bf16 v[32:35], v[186:189], v[234:237], v[32:35]
	s_setprio 0
	s_setprio 1
	v_mfma_f32_16x16x32_bf16 v[126:129], v[190:193], v[206:209], v[126:129]
	v_mfma_f32_16x16x32_bf16 v[122:125], v[198:201], v[206:209], v[122:125]
	v_mfma_f32_16x16x32_bf16 v[118:121], v[190:193], v[214:217], v[118:121]
	v_mfma_f32_16x16x32_bf16 v[114:117], v[198:201], v[214:217], v[114:117]
	v_mfma_f32_16x16x32_bf16 v[110:113], v[190:193], v[222:225], v[110:113]
	v_mfma_f32_16x16x32_bf16 v[106:109], v[198:201], v[222:225], v[106:109]
	v_mfma_f32_16x16x32_bf16 v[102:105], v[190:193], v[230:233], v[102:105]
	v_mfma_f32_16x16x32_bf16 v[98:101], v[198:201], v[230:233], v[98:101]
	v_mfma_f32_16x16x32_bf16 v[126:129], v[194:197], v[210:213], v[126:129]
	v_mfma_f32_16x16x32_bf16 v[122:125], v[202:205], v[210:213], v[122:125]
	v_mfma_f32_16x16x32_bf16 v[118:121], v[194:197], v[218:221], v[118:121]
	v_mfma_f32_16x16x32_bf16 v[114:117], v[202:205], v[218:221], v[114:117]
	v_mfma_f32_16x16x32_bf16 v[110:113], v[194:197], v[226:229], v[110:113]
	v_mfma_f32_16x16x32_bf16 v[106:109], v[202:205], v[226:229], v[106:109]
	v_mfma_f32_16x16x32_bf16 v[102:105], v[194:197], v[234:237], v[102:105]
	v_mfma_f32_16x16x32_bf16 v[98:101], v[202:205], v[234:237], v[98:101]
	s_setprio 0
	s_barrier
; #define PG8_STAGE(bufoff, gbase, voff) do { _Pragma("unroll") for (int _i = 0; _i < 2; ++_i) \
;         __builtin_amdgcn_global_load_lds((const unsigned*)((const char*)(gbase) + (voff)[_i]), (PG8_LAS unsigned*)(lds + (bufoff) + ldsw + _i * 8192), 16, 0, 0); } while (0)
; #define PG8_LDA(dst, b, h) do { _Pragma("unroll") for (int m = 0; m < 4; ++m) _Pragma("unroll") for (int k = 0; k < 2; ++k) dst[m][k] = *(const PG8_LAS bf16x8*)(lds + PG8_SA(b, h) + aoff + m * 2048 + k * 1024); } while (0)
; #define PG8_MMA(ai, bj, At, Bt) do { __builtin_amdgcn_s_setprio(1); _Pragma("unroll") for (int m = 0; m < 4; ++m) _Pragma("unroll") for (int n = 0; n < 2; ++n) _Pragma("unroll") for (int k = 0; k < 2; ++k) \
;         acc[ai][bj][m][n] = __builtin_amdgcn_mfma_f32_16x16x32_bf16(Bt[n][k], At[m][k], acc[ai][bj][m][n], 0, 0, 0); __builtin_amdgcn_s_setprio(0); } while (0)
; #define PG8_WAIT_V(n) asm volatile("s_waitcnt vmcnt(" #n ")" ::: "memory")
; #define PG8_WAIT_L(n) asm volatile("s_waitcnt lgkmcnt(" #n ")" ::: "memory")
; #define PG8_BAR __builtin_amdgcn_s_barrier()
; #define PG8_SCHED __builtin_amdgcn_sched_barrier(0)
; template <class Epi, class Sched, bool ALIGN_EPI = false, bool SP2 = false>
; __device__ __forceinline__ void gemm_phase(PG8_LAS unsigned char* lds, const Gemm g, const Sched& S, const Epi& E) {
;     ...
;         for (int t = 0; t < nt; t += 2) {
;     ...
;             PG8_LDA(At, 1, 1); PG8_STAGE(PG8_SB(1, 0), b3, voffB); PG8_STAGE(PG8_SB(1, 1), b3 + hstep, voffB); PG8_STAGE(PG8_SA(1, 0), a3, voffA);
;             PG8_WAIT_V(8); PG8_WAIT_L(0); PG8_BAR; PG8_MMA(1, 0, At, B0); PG8_MMA(1, 1, At, B1); PG8_BAR; PG8_SCHED;
	s_add_i32 s35, s35, s49
	v_lshl_add_u64 v[68:69], v[156:157], 0, s[16:17]
	s_mov_b32 m0, s35
	ds_read_b128 v[206:209], v176 offset:49152
	ds_read_b128 v[210:213], v176 offset:50176
	ds_read_b128 v[214:217], v176 offset:51200
	ds_read_b128 v[218:221], v176 offset:52224
	ds_read_b128 v[222:225], v176 offset:53248
	ds_read_b128 v[226:229], v176 offset:54272
	ds_read_b128 v[230:233], v176 offset:55296
	ds_read_b128 v[234:237], v176 offset:56320
	global_load_lds_dwordx4 v[68:69], off
	s_add_i32 m0, s35, 0x2000
	s_add_u32 s42, s42, 0x80080
	v_lshl_add_u64 v[68:69], v[238:239], 0, s[16:17]
	s_addc_u32 s43, s43, 0
	s_add_i32 s35, s56, s49
	global_load_lds_dwordx4 v[68:69], off
	v_lshl_add_u64 v[68:69], s[42:43], 0, v[136:137]
	s_mov_b32 m0, s35
	s_nop 0
	global_load_lds_dwordx4 v[68:69], off
	v_lshl_add_u64 v[68:69], s[42:43], 0, v[140:141]
	s_add_i32 m0, s35, 0x2000
	s_nop 0
	global_load_lds_dwordx4 v[68:69], off
	v_lshl_add_u64 v[68:69], v[240:241], 0, s[16:17]
	s_mov_b32 m0, s67
	s_nop 0
	global_load_lds_dwordx4 v[68:69], off
	v_lshl_add_u64 v[68:69], v[242:243], 0, s[16:17]
	s_mov_b32 m0, s68
	s_nop 0
	global_load_lds_dwordx4 v[68:69], off
	s_waitcnt vmcnt(8)
	s_waitcnt lgkmcnt(0)
	s_barrier
	s_setprio 1
	s_waitcnt lgkmcnt(0)
	v_mfma_f32_16x16x32_bf16 v[28:31], v[130:133], v[206:209], v[28:31]
	v_mfma_f32_16x16x32_bf16 v[24:27], v[182:185], v[206:209], v[24:27]
	v_mfma_f32_16x16x32_bf16 v[20:23], v[130:133], v[214:217], v[20:23]
	v_mfma_f32_16x16x32_bf16 v[16:19], v[182:185], v[214:217], v[16:19]
	v_mfma_f32_16x16x32_bf16 v[12:15], v[130:133], v[222:225], v[12:15]
	v_mfma_f32_16x16x32_bf16 v[8:11], v[182:185], v[222:225], v[8:11]
	v_mfma_f32_16x16x32_bf16 v[4:7], v[130:133], v[230:233], v[4:7]
	v_mfma_f32_16x16x32_bf16 v[0:3], v[182:185], v[230:233], v[0:3]
	v_mfma_f32_16x16x32_bf16 v[28:31], v[178:181], v[210:213], v[28:31]
	v_mfma_f32_16x16x32_bf16 v[24:27], v[186:189], v[210:213], v[24:27]
	v_mfma_f32_16x16x32_bf16 v[20:23], v[178:181], v[218:221], v[20:23]
	v_mfma_f32_16x16x32_bf16 v[16:19], v[186:189], v[218:221], v[16:19]
	v_mfma_f32_16x16x32_bf16 v[12:15], v[178:181], v[226:229], v[12:15]
	v_mfma_f32_16x16x32_bf16 v[8:11], v[186:189], v[226:229], v[8:11]
	v_mfma_f32_16x16x32_bf16 v[4:7], v[178:181], v[234:237], v[4:7]
	v_mfma_f32_16x16x32_bf16 v[0:3], v[186:189], v[234:237], v[0:3]
	s_setprio 0
	s_setprio 1
	v_mfma_f32_16x16x32_bf16 v[94:97], v[190:193], v[206:209], v[94:97]
	v_mfma_f32_16x16x32_bf16 v[90:93], v[198:201], v[206:209], v[90:93]
	v_mfma_f32_16x16x32_bf16 v[86:89], v[190:193], v[214:217], v[86:89]
	v_mfma_f32_16x16x32_bf16 v[82:85], v[198:201], v[214:217], v[82:85]
	v_mfma_f32_16x16x32_bf16 v[78:81], v[190:193], v[222:225], v[78:81]
	v_mfma_f32_16x16x32_bf16 v[68:71], v[198:201], v[222:225], v[70:73]
	v_mfma_f32_16x16x32_bf16 v[74:77], v[190:193], v[230:233], v[74:77]
	v_mfma_f32_16x16x32_bf16 v[64:67], v[198:201], v[230:233], v[64:67]
	v_mfma_f32_16x16x32_bf16 v[94:97], v[194:197], v[210:213], v[94:97]
	v_mfma_f32_16x16x32_bf16 v[90:93], v[202:205], v[210:213], v[90:93]
	v_mfma_f32_16x16x32_bf16 v[86:89], v[194:197], v[218:221], v[86:89]
	v_mfma_f32_16x16x32_bf16 v[82:85], v[202:205], v[218:221], v[82:85]
	v_mfma_f32_16x16x32_bf16 v[78:81], v[194:197], v[226:229], v[78:81]
	v_mfma_f32_16x16x32_bf16 v[70:73], v[202:205], v[226:229], v[68:71]
	v_mfma_f32_16x16x32_bf16 v[74:77], v[194:197], v[234:237], v[74:77]
	v_mfma_f32_16x16x32_bf16 v[66:69], v[202:205], v[234:237], v[64:67]
	s_setprio 0
	s_barrier
	s_add_i32 s33, s33, 2
	s_add_u32 s40, s40, 0x100
	s_addc_u32 s41, s41, 0
	s_add_u32 s13, s13, 0x100
	s_addc_u32 s31, s31, 0
	s_cmp_gt_u32 s33, 29
	s_branch .LBB0_188

; #define PG8_STAGE(bufoff, gbase, voff) do { _Pragma("unroll") for (int _i = 0; _i < 2; ++_i) \
;         __builtin_amdgcn_global_load_lds((const unsigned*)((const char*)(gbase) + (voff)[_i]), (PG8_LAS unsigned*)(lds + (bufoff) + ldsw + _i * 8192), 16, 0, 0); } while (0)
; #define PG8_LDA(dst, b, h) do { _Pragma("unroll") for (int m = 0; m < 4; ++m) _Pragma("unroll") for (int k = 0; k < 2; ++k) dst[m][k] = *(const PG8_LAS bf16x8*)(lds + PG8_SA(b, h) + aoff + m * 2048 + k * 1024); } while (0)
; #define PG8_LDB(dst, b, h) do { _Pragma("unroll") for (int n = 0; n < 2; ++n) _Pragma("unroll") for (int k = 0; k < 2; ++k) dst[n][k] = *(const PG8_LAS bf16x8*)(lds + PG8_SB(b, h) + boff + n * 2048 + k * 1024); } while (0)
; #define PG8_SCHED __builtin_amdgcn_sched_barrier(0)
; template <class Epi, class Sched, bool ALIGN_EPI = false, bool SP2 = false>
; __device__ __forceinline__ void gemm_phase(PG8_LAS unsigned char* lds, const Gemm g, const Sched& S, const Epi& E) {
;     ...
;             const char* a2 = last ? nA : cA + (size_t)(t + 2) * kstep; const char* b2 = last ? nB : cB + (size_t)(t + 2) * kstep;
;             const char* a3 = a2 + kstep; const char* b3 = b2 + kstep;
;             if (last && has_next) S.a_ready(nxt);
;             if constexpr (SP2) {
;             PG8_LDB(B0, 0, 0); PG8_LDB(B1, 0, 1); PG8_SCHED; PG8_LDA(At, 0, 0); PG8_STAGE(PG8_SA(1, 1), a1 + hstep, voffA);
.LBB0_191:
	s_cmp_lg_u32 s6, 56
	s_cselect_b32 s58, 1, 0
	s_cbranch_scc0 .Lp2_nohoist
	s_add_u32 vcc_lo, s3, 0x80080
	s_addc_u32 vcc_hi, s1, 0
	v_lshl_add_u64 v[244:245], vcc, 0, v[148:149]
	s_add_i32 m0, s50, 0xc000
	v_lshl_add_u64 v[246:247], vcc, 0, v[150:151]
	global_load_lds_dwordx4 v[244:245], off
	s_add_i32 m0, s50, 0xe000
	s_nop 0
	global_load_lds_dwordx4 v[246:247], off
